# mlstm_out unit prologue: the 16 Q/Ka tile piece loads issued together (were 8 serial load-wait-write pairs)
# speedup vs baseline: 1.0050x; 1.0010x over previous
.LBB0_578:
	s_lshl_b32 s43, s50, 5
	s_and_b32 s42, s50, 0xffffff00
	s_and_b32 s43, s43, 0xe0
	s_or_b32 s42, s43, s42
	s_bfe_u32 s43, s50, 0x50003
	s_or_b32 s44, s42, s43
	s_and_b64 s[42:43], s[58:59], exec
	s_cselect_b32 s42, s44, s50
	s_and_b32 s51, s42, 1
	s_ashr_i32 s62, s42, 9
	s_bfe_u32 s80, s42, 0x50001
	s_bfe_u32 s81, s42, 0x30006
	s_ashr_i32 s63, s62, 31
	s_lshl_b32 s42, s51, 2
	s_lshl_b64 s[60:61], s[62:63], 12
	s_lshl_b32 s82, s80, 7
	s_add_i32 s44, s42, s62
	s_or_b32 s60, s60, s82
	s_ashr_i32 s45, s44, 31
	s_lshl_b32 s83, s81, 5
	s_cmp_eq_u32 s51, 0
	s_cselect_b64 s[42:43], -1, 0
	s_and_b64 s[46:47], s[42:43], exec
	s_mov_b32 s46, 0x59000000
	s_cselect_b32 s46, s46, 0x5d000000
	v_mov_b32_e32 v3, s61
	v_or_b32_e32 v2, s60, v166
	s_add_u32 s46, s68, s46
	v_lshlrev_b64 v[2:3], 11, v[2:3]
	s_addc_u32 s47, s69, 0
	s_lshl_b32 vcc_lo, s81, 8
	v_or_b32_e32 v2, v2, v168
	v_or_b32_e32 v2, vcc_lo, v2
	v_lshlrev_b64 v[6:7], 1, v[2:3]
	v_lshl_add_u64 v[2:3], s[52:53], 0, v[6:7]
	s_barrier
	global_load_dwordx4 v[10:13], v[2:3], off
	v_lshl_add_u64 v[6:7], s[46:47], 0, v[6:7]
	global_load_dwordx4 v[14:17], v[6:7], off
	s_lshl_b64 s[44:45], s[44:45], 8
	s_or_b32 s44, s44, s83
	s_or_b32 s44, s44, s80
	v_mov_b32_e32 v3, s61
	v_or_b32_e32 v2, s60, v170
	v_lshlrev_b64 v[2:3], 11, v[2:3]
	v_or_b32_e32 v2, v2, v168
	v_or_b32_e32 v2, vcc_lo, v2
	v_lshlrev_b64 v[6:7], 1, v[2:3]
	v_lshl_add_u64 v[2:3], s[52:53], 0, v[6:7]
	global_load_dwordx4 v[18:21], v[2:3], off
	v_lshl_add_u64 v[6:7], s[46:47], 0, v[6:7]
	global_load_dwordx4 v[22:25], v[6:7], off
	v_mov_b32_e32 v3, s61
	v_or_b32_e32 v2, s60, v172
	v_lshlrev_b64 v[2:3], 11, v[2:3]
	v_or_b32_e32 v2, v2, v168
	v_or_b32_e32 v2, vcc_lo, v2
	v_lshlrev_b64 v[6:7], 1, v[2:3]
	v_lshl_add_u64 v[2:3], s[52:53], 0, v[6:7]
	global_load_dwordx4 v[26:29], v[2:3], off
	v_lshl_add_u64 v[6:7], s[46:47], 0, v[6:7]
	global_load_dwordx4 v[30:33], v[6:7], off
	v_mov_b32_e32 v3, s61
	v_or_b32_e32 v2, s60, v174
	v_lshlrev_b64 v[2:3], 11, v[2:3]
	v_or_b32_e32 v2, v2, v168
	v_or_b32_e32 v2, vcc_lo, v2
	v_lshlrev_b64 v[6:7], 1, v[2:3]
	v_lshl_add_u64 v[2:3], s[52:53], 0, v[6:7]
	global_load_dwordx4 v[34:37], v[2:3], off
	v_lshl_add_u64 v[6:7], s[46:47], 0, v[6:7]
	global_load_dwordx4 v[38:41], v[6:7], off
	v_mov_b32_e32 v3, s61
	v_or_b32_e32 v2, s60, v176
	v_lshlrev_b64 v[2:3], 11, v[2:3]
	v_or_b32_e32 v2, v2, v168
	v_or_b32_e32 v2, vcc_lo, v2
	v_lshlrev_b64 v[6:7], 1, v[2:3]
	v_lshl_add_u64 v[2:3], s[52:53], 0, v[6:7]
	global_load_dwordx4 v[42:45], v[2:3], off
	v_lshl_add_u64 v[6:7], s[46:47], 0, v[6:7]
	global_load_dwordx4 v[46:49], v[6:7], off
	v_mov_b32_e32 v3, s61
	v_or_b32_e32 v2, s60, v178
	v_lshlrev_b64 v[2:3], 11, v[2:3]
	v_or_b32_e32 v2, v2, v168
	v_or_b32_e32 v2, vcc_lo, v2
	v_lshlrev_b64 v[6:7], 1, v[2:3]
	v_lshl_add_u64 v[2:3], s[52:53], 0, v[6:7]
	global_load_dwordx4 v[50:53], v[2:3], off
	v_lshl_add_u64 v[6:7], s[46:47], 0, v[6:7]
	global_load_dwordx4 v[54:57], v[6:7], off
	v_mov_b32_e32 v3, s61
	v_or_b32_e32 v2, s60, v180
	v_lshlrev_b64 v[2:3], 11, v[2:3]
	v_or_b32_e32 v2, v2, v168
	v_or_b32_e32 v2, vcc_lo, v2
	v_lshlrev_b64 v[6:7], 1, v[2:3]
	v_lshl_add_u64 v[2:3], s[52:53], 0, v[6:7]
	global_load_dwordx4 v[58:61], v[2:3], off
	v_lshl_add_u64 v[6:7], s[46:47], 0, v[6:7]
	global_load_dwordx4 v[62:65], v[6:7], off
	v_mov_b32_e32 v3, s61
	v_or_b32_e32 v2, s60, v182
	v_lshlrev_b64 v[2:3], 11, v[2:3]
	v_or_b32_e32 v2, v2, v168
	v_or_b32_e32 v2, vcc_lo, v2
	v_lshlrev_b64 v[6:7], 1, v[2:3]
	v_lshl_add_u64 v[2:3], s[52:53], 0, v[6:7]
	global_load_dwordx4 v[66:69], v[2:3], off
	v_lshl_add_u64 v[6:7], s[46:47], 0, v[6:7]
	global_load_dwordx4 v[70:73], v[6:7], off
	v_add_u32_e32 v74, v208, v207
	s_waitcnt vmcnt(15)
	ds_write_b128 v221, v[10:13]
	s_waitcnt vmcnt(14)
	ds_write_b128 v74, v[14:17]
	s_waitcnt vmcnt(13)
	ds_write_b128 v222, v[18:21]
	s_waitcnt vmcnt(12)
	ds_write_b128 v223, v[22:25]
	s_waitcnt vmcnt(11)
	ds_write_b128 v221, v[26:29] offset:16896
	s_waitcnt vmcnt(10)
	ds_write_b128 v224, v[30:33]
	s_waitcnt vmcnt(9)
	ds_write_b128 v225, v[34:37]
	s_waitcnt vmcnt(8)
	ds_write_b128 v226, v[38:41]
	s_waitcnt vmcnt(7)
	ds_write_b128 v221, v[42:45] offset:33792
	s_waitcnt vmcnt(6)
	ds_write_b128 v227, v[46:49]
	s_waitcnt vmcnt(5)
	ds_write_b128 v228, v[50:53]
	s_waitcnt vmcnt(4)
	ds_write_b128 v229, v[54:57]
	s_waitcnt vmcnt(3)
	ds_write_b128 v221, v[58:61] offset:50688
	s_waitcnt vmcnt(2)
	ds_write_b128 v230, v[62:65]
	s_waitcnt vmcnt(1)
	ds_write_b128 v231, v[66:69]
	s_waitcnt vmcnt(0)
	ds_write_b128 v232, v[70:73]
	s_and_saveexec_b64 s[46:47], s[38:39]
	s_xor_b64 s[46:47], exec, s[46:47]
	s_cbranch_execz .LBB0_582
	s_mov_b32 s83, s85
	s_mov_b64 vcc, exec
	v_readlane_b32 s84, v255, 51
	v_readlane_b32 s85, v255, 52
	s_and_b64 s[84:85], vcc, s[84:85]
	s_mov_b64 exec, s[84:85]
	s_cbranch_execz .LBB0_581
	s_lshl_b64 s[84:85], s[44:45], 10
	v_lshl_add_u64 v[2:3], v[184:185], 0, s[84:85]
	global_load_dwordx4 v[2:5], v[2:3], off
	s_waitcnt vmcnt(0)
	ds_write_b128 v209, v[2:5]
